# prologue silu(c) staging loop de-serialised: 16 loads in flight with counted vmcnt instead of load+vmcnt(0) per element
# speedup vs baseline: 1.0121x; 1.0121x over previous
.LBB0_1579:
	s_mov_b64 s[8:9], 0x1000
	global_load_dword v112, v[2:3], off
	global_load_dword v113, v[2:3], off offset:2048
	v_lshl_add_u64 v[2:3], v[2:3], 0, s[8:9]
	global_load_dword v114, v[2:3], off
	global_load_dword v115, v[2:3], off offset:2048
	v_lshl_add_u64 v[2:3], v[2:3], 0, s[8:9]
	global_load_dword v116, v[2:3], off
	global_load_dword v117, v[2:3], off offset:2048
	v_lshl_add_u64 v[2:3], v[2:3], 0, s[8:9]
	global_load_dword v118, v[2:3], off
	global_load_dword v119, v[2:3], off offset:2048
	v_lshl_add_u64 v[2:3], v[2:3], 0, s[8:9]
	global_load_dword v120, v[2:3], off
	global_load_dword v121, v[2:3], off offset:2048
	v_lshl_add_u64 v[2:3], v[2:3], 0, s[8:9]
	global_load_dword v122, v[2:3], off
	global_load_dword v123, v[2:3], off offset:2048
	v_lshl_add_u64 v[2:3], v[2:3], 0, s[8:9]
	global_load_dword v124, v[2:3], off
	global_load_dword v125, v[2:3], off offset:2048
	v_lshl_add_u64 v[2:3], v[2:3], 0, s[8:9]
	global_load_dword v126, v[2:3], off
	global_load_dword v127, v[2:3], off offset:2048
	s_waitcnt vmcnt(15)
	v_mul_f32_e32 v6, 0xbfb8aa3b, v112
	v_exp_f32_e32 v6, v6
	s_nop 0
	v_add_f32_e32 v6, 1.0, v6
	v_rcp_f32_e32 v6, v6
	s_nop 0
	v_mul_f32_e32 v5, v112, v6
	ds_write_b32 v4, v5
	s_waitcnt vmcnt(14)
	v_mul_f32_e32 v6, 0xbfb8aa3b, v113
	v_exp_f32_e32 v6, v6
	s_nop 0
	v_add_f32_e32 v6, 1.0, v6
	v_rcp_f32_e32 v6, v6
	s_nop 0
	v_mul_f32_e32 v5, v113, v6
	ds_write_b32 v4, v5 offset:2048
	s_waitcnt vmcnt(13)
	v_mul_f32_e32 v6, 0xbfb8aa3b, v114
	v_exp_f32_e32 v6, v6
	s_nop 0
	v_add_f32_e32 v6, 1.0, v6
	v_rcp_f32_e32 v6, v6
	s_nop 0
	v_mul_f32_e32 v5, v114, v6
	ds_write_b32 v4, v5 offset:4096
	s_waitcnt vmcnt(12)
	v_mul_f32_e32 v6, 0xbfb8aa3b, v115
	v_exp_f32_e32 v6, v6
	s_nop 0
	v_add_f32_e32 v6, 1.0, v6
	v_rcp_f32_e32 v6, v6
	s_nop 0
	v_mul_f32_e32 v5, v115, v6
	ds_write_b32 v4, v5 offset:6144
	s_waitcnt vmcnt(11)
	v_mul_f32_e32 v6, 0xbfb8aa3b, v116
	v_exp_f32_e32 v6, v6
	s_nop 0
	v_add_f32_e32 v6, 1.0, v6
	v_rcp_f32_e32 v6, v6
	s_nop 0
	v_mul_f32_e32 v5, v116, v6
	ds_write_b32 v4, v5 offset:8192
	s_waitcnt vmcnt(10)
	v_mul_f32_e32 v6, 0xbfb8aa3b, v117
	v_exp_f32_e32 v6, v6
	s_nop 0
	v_add_f32_e32 v6, 1.0, v6
	v_rcp_f32_e32 v6, v6
	s_nop 0
	v_mul_f32_e32 v5, v117, v6
	ds_write_b32 v4, v5 offset:10240
	s_waitcnt vmcnt(9)
	v_mul_f32_e32 v6, 0xbfb8aa3b, v118
	v_exp_f32_e32 v6, v6
	s_nop 0
	v_add_f32_e32 v6, 1.0, v6
	v_rcp_f32_e32 v6, v6
	s_nop 0
	v_mul_f32_e32 v5, v118, v6
	ds_write_b32 v4, v5 offset:12288
	s_waitcnt vmcnt(8)
	v_mul_f32_e32 v6, 0xbfb8aa3b, v119
	v_exp_f32_e32 v6, v6
	s_nop 0
	v_add_f32_e32 v6, 1.0, v6
	v_rcp_f32_e32 v6, v6
	s_nop 0
	v_mul_f32_e32 v5, v119, v6
	ds_write_b32 v4, v5 offset:14336
	s_waitcnt vmcnt(7)
	v_mul_f32_e32 v6, 0xbfb8aa3b, v120
	v_exp_f32_e32 v6, v6
	s_nop 0
	v_add_f32_e32 v6, 1.0, v6
	v_rcp_f32_e32 v6, v6
	s_nop 0
	v_mul_f32_e32 v5, v120, v6
	ds_write_b32 v4, v5 offset:16384
	s_waitcnt vmcnt(6)
	v_mul_f32_e32 v6, 0xbfb8aa3b, v121
	v_exp_f32_e32 v6, v6
	s_nop 0
	v_add_f32_e32 v6, 1.0, v6
	v_rcp_f32_e32 v6, v6
	s_nop 0
	v_mul_f32_e32 v5, v121, v6
	ds_write_b32 v4, v5 offset:18432
	s_waitcnt vmcnt(5)
	v_mul_f32_e32 v6, 0xbfb8aa3b, v122
	v_exp_f32_e32 v6, v6
	s_nop 0
	v_add_f32_e32 v6, 1.0, v6
	v_rcp_f32_e32 v6, v6
	s_nop 0
	v_mul_f32_e32 v5, v122, v6
	ds_write_b32 v4, v5 offset:20480
	s_waitcnt vmcnt(4)
	v_mul_f32_e32 v6, 0xbfb8aa3b, v123
	v_exp_f32_e32 v6, v6
	s_nop 0
	v_add_f32_e32 v6, 1.0, v6
	v_rcp_f32_e32 v6, v6
	s_nop 0
	v_mul_f32_e32 v5, v123, v6
	ds_write_b32 v4, v5 offset:22528
	s_waitcnt vmcnt(3)
	v_mul_f32_e32 v6, 0xbfb8aa3b, v124
	v_exp_f32_e32 v6, v6
	s_nop 0
	v_add_f32_e32 v6, 1.0, v6
	v_rcp_f32_e32 v6, v6
	s_nop 0
	v_mul_f32_e32 v5, v124, v6
	ds_write_b32 v4, v5 offset:24576
	s_waitcnt vmcnt(2)
	v_mul_f32_e32 v6, 0xbfb8aa3b, v125
	v_exp_f32_e32 v6, v6
	s_nop 0
	v_add_f32_e32 v6, 1.0, v6
	v_rcp_f32_e32 v6, v6
	s_nop 0
	v_mul_f32_e32 v5, v125, v6
	ds_write_b32 v4, v5 offset:26624
	s_waitcnt vmcnt(1)
	v_mul_f32_e32 v6, 0xbfb8aa3b, v126
	v_exp_f32_e32 v6, v6
	s_nop 0
	v_add_f32_e32 v6, 1.0, v6
	v_rcp_f32_e32 v6, v6
	s_nop 0
	v_mul_f32_e32 v5, v126, v6
	ds_write_b32 v4, v5 offset:28672
	s_waitcnt vmcnt(0)
	v_mul_f32_e32 v6, 0xbfb8aa3b, v127
	v_exp_f32_e32 v6, v6
	s_nop 0
	v_add_f32_e32 v6, 1.0, v6
	v_rcp_f32_e32 v6, v6
	s_nop 0
	v_mul_f32_e32 v5, v127, v6
	ds_write_b32 v4, v5 offset:30720
